# no entry grid.sync + up-GEMM 2-group stagger, 4x s_sleep 127 (~13us)
# baseline (speedup 1.0000x reference)
; __global__ void __launch_bounds__(512, 2) mega_fwd(Args args) {
;     ...
;     for (int ph = args.ph_lo; ph < args.ph_hi; ++ph) {
;         const int l = ph / PH_PER_LAYER, k = ph % PH_PER_LAYER;
;         { int t_ = threadIdx.x; asm volatile("" : "+v"(t_)); c.tid = t_; c.lane = t_ & 63; c.wave = __builtin_amdgcn_readfirstlane(t_ >> 6);
;           int z_ = 0; asm volatile("" : "+s"(z_)); c.zero = z_;
;           int bx = blockIdx.x; asm volatile("" : "+s"(bx)); c.vcu = (c.G % 8 == 0) ? (bx % 8) * (c.G / 8) + bx / 8 : bx; }
;     ...
;         if (k == 0) {
;     ...
;         } else if (k == 5) {
;             pg8::Gemm g{XB, (const bf16_t*)(c.ws + WS_WUP), MTOK, 1024, 1024}; pg8::StaticOrder S; S.init(MTOK, 1024, c.G, (int)blockIdx.x);
;             pg8::EpiUp E{(const bf16_t*)(c.ws + WS_Z + 6 * ZARR), (bf16_t*)(c.ws + WS_Z + 1 * ZARR)};
;             int nrep_ = (REPMASK & 32) ? 2 : 1; asm volatile("" : "+s"(nrep_));
;             for (int r_ = 0; r_ < nrep_; ++r_) { if (PHMASK & 32) pg8::gemm_phase<pg8::EpiUp, pg8::StaticOrder, true, true>(lds3, g, S, E); __syncthreads(); }
.LBB0_22:
	v_readlane_b32 s12, v253, 4
	s_mul_hi_i32 s0, s12, 0x92492493
	s_add_i32 s0, s0, s12
	s_lshr_b32 s6, s0, 31
	s_ashr_i32 s0, s0, 2
	s_add_i32 s80, s0, s6
	s_mul_i32 s0, s80, 7
	v_readlane_b32 s13, v253, 5
	s_sub_i32 s92, s12, s0
	v_writelane_b32 v252, s16, 46
	s_ashr_i32 s0, s16, 6
	v_and_b32_e32 v200, 63, v201
	v_writelane_b32 v252, s0, 47
	s_mov_b64 s[38:39], -1
	s_mov_b64 s[12:13], 0
	s_cmp_lt_i32 s92, 3
	s_mov_b64 s[76:77], 0
	v_writelane_b32 v252, s24, 48
	s_cbranch_scc1 .LBB0_308
	s_cmp_gt_i32 s92, 3
	v_writelane_b32 v252, s92, 49
	s_cbranch_scc0 .LBB0_90
	s_cmp_gt_i32 s92, 4
	s_cbranch_scc0 .LBB0_62
	s_cmp_eq_u32 s92, 5
	s_mov_b64 s[76:77], -1
	s_cbranch_scc0 .LBB0_61
	s_lshr_b32 s98, s2, 3
	s_and_b32 s98, s98, 1
	s_mul_i32 s98, s98, 4
	s_cmp_eq_u32 s98, 0
	s_cbranch_scc1 .Lstag5_done
